# attnA loop head segment (staging, K reads, QK-A) shifted by 4 bytes, later segments unchanged: code-placement trial
# speedup vs baseline: 1.0003x; 1.0003x over previous
; DI int ltid_w(int wave) { int t; asm volatile("v_mbcnt_lo_u32_b32 %0, -1, 0\n\tv_mbcnt_hi_u32_b32 %0, -1, %0" : "=v"(t)); return (wave << 6) | t; }
; template <int MODE>
; DI void attn_mfma(const Params& p, int l, int b, int hd, int qb, unsigned char* smem) {
;     ...
;   const int tid = ltid_w(p.wave), lane = tid & 63, wv = tid >> 6, r = lane & 31, h2 = lane >> 5;
;   const int mp = MODE ? 0 : (wv >> 1);
;   const bf16_t* P = (const bf16_t*)(p.ws + WS_P);
;   bf16_t* MIX = (bf16_t*)(p.ws + WS_HM);
;   const int kvh = MODE ? (hd >> 1) : hd;
;   const bf16_t* VT = MODE ? (const bf16_t*)(p.ws + WS_VTC) + ((size_t)(b * 2 + kvh) * 64) * NTOK : (const bf16_t*)(p.ws + WS_VTA) + ((size_t)(b * 4 + hd) * 64) * NTOK;
;   const int qcol = MODE ? C_Q + hd * 64 : A_Q + hd * 64;
;   const int kcol = MODE ? C_K + kvh * 64 : A_K + hd * 64;
;   unsigned char* sK = smem;
;   unsigned char* sV = smem + 8192;
;   const int tq = qb * QPB + (MODE ? wv : (wv & 1)) * 32 + r;
;   const size_t qrow = (size_t)b * NTOK + tq;
;   bf16x8 qf[KS];
; #pragma unroll
;   for (int ks = 0; ks < KS; ++ks) qf[ks] = *(const bf16x8*)(P + qrow * PW + qcol + (2 * (mp * 2 + ks) + h2) * 8);
;   const bool isctx = qb * QPB < NCTX;
;   int ntiles, band_lo = 0;
;   if (MODE == 0) ntiles = isctx ? 4 : 36;
;   else {
;     if (isctx) ntiles = 4;
;     else { const int i0 = qb * QPB - NCTX; int lo = i0 - 128; if (lo < 0) lo = 0; int hi = i0 + 256; if (hi > NLAT) hi = NLAT; band_lo = lo; ntiles = 4 + (hi - lo) / 64; }
;   }
;   const float cexp = (MODE ? 0.125f : 0.17677669529663687f) * 1.4426950408889634f;
;   float mrun = MODE ? p.sw_sink[l * 4 + hd] * 1.4426950408889634f : -1e30f;
;   float lsum = (MODE && h2 == 0) ? 1.f : 0.f;
;   f32x16 O[2];
; #pragma unroll
;   for (int vt = 0; vt < 2; ++vt)
; #pragma unroll
;     for (int i = 0; i < 16; ++i) O[vt][i] = 0.f;
;   const int lrow = tid >> 3, lc = tid & 7;
;   auto tile_base = [&](int j) -> int { return (MODE == 0 || j < 4) ? j * 64 : NCTX + band_lo + (j - 4) * 64; };
;   uint4 gk00, gk01, gk10, gk11, gv00, gv01, gv10, gv11;
;     ...
;   ATT_LOAD(tile_base(0), gk00, gk01, gv00, gv01);
;   ATT_LOAD(tile_base(1), gk10, gk11, gv10, gv11);
.LBB0_575:
	s_andn2_b64 vcc, exec, s[0:1]
	s_cbranch_vccnz .LBB0_591
	s_add_i32 s0, s46, 0xffc0
	s_and_b32 s8, s0, 0xffff
	s_mul_i32 s1, s8, 0xe38f
	s_lshr_b32 s5, s1, 21
	s_mul_i32 s1, s5, 36
	s_sub_i32 s2, s0, s1
	s_and_b32 s0, s2, 0xffff
	s_cmp_lt_u32 s0, 4
	v_readlane_b32 s6, v254, 12
	s_cselect_b64 s[0:1], -1, 0
	v_readlane_b32 s7, v254, 13
	s_and_b64 s[6:7], s[6:7], s[0:1]
	s_and_b64 vcc, exec, s[6:7]
	s_cbranch_vccnz .LBB0_591
	s_and_b32 s4, 0xffff, s5
	s_lshr_b32 s9, s4, 2
	s_and_b32 s6, s4, 3
	v_readlane_b32 s4, v253, 39
	s_add_u32 s10, s40, 0x41c6000
	v_mbcnt_lo_u32_b32 v6, -1, 0
	v_mbcnt_hi_u32_b32 v6, -1, v6
	s_addc_u32 s11, s41, 0
	v_or_b32_e32 v196, s4, v6
	s_lshl_b32 s4, s9, 8
	s_lshl_b32 s7, s6, 6
	s_or_b32 s4, s7, s4
	s_mulk_i32 s4, 0x1200
	s_add_u32 s4, s40, s4
	s_addc_u32 s13, s41, 0
	s_add_u32 s12, s4, 0xef06000
	s_addc_u32 s13, s13, 0
	s_lshl_b32 s2, s2, 6
	s_and_b32 s2, s2, 0xffc0
	v_lshrrev_b32_e32 v0, 1, v196
	s_mul_i32 s14, s9, 0x900
	v_and_b32_e32 v198, 31, v6
	v_and_b32_e32 v199, 32, v0
	s_add_i32 s2, s14, s2
	v_bfe_u32 v171, v6, 5, 1
	v_or3_b32 v165, v198, s2, v199
	v_ashrrev_i32_e32 v197, 7, v196
	v_mul_lo_u32 v160, v165, s33
	v_lshlrev_b32_e32 v164, 3, v171
	v_lshl_add_u64 v[166:167], s[10:11], 0, v[160:161]
	s_lshl_b32 s2, s6, 7
	v_lshl_or_b32 v2, v197, 5, v164
	v_lshl_add_u64 v[0:1], v[166:167], 0, s[2:3]
	v_ashrrev_i32_e32 v3, 31, v2
	v_lshl_add_u64 v[0:1], v[2:3], 1, v[0:1]
	v_ashrrev_i32_e32 v8, 3, v196
	s_waitcnt vmcnt(0)
	global_load_dwordx4 v[96:99], v[0:1], off
	global_load_dwordx4 v[100:103], v[0:1], off offset:32
	v_add_u32_e32 v7, s14, v8
	v_mov_b64_e32 v[0:1], s[10:11]
	v_lshlrev_b32_e32 v9, 4, v6
	s_and_b64 s[0:1], s[0:1], exec
	v_mad_i64_i32 v[2:3], s[0:1], v7, s33, v[0:1]
	v_and_b32_e32 v160, 0x70, v9
	s_cselect_b32 s4, 4, 36
	v_lshl_add_u64 v[4:5], v[2:3], 0, s[2:3]
	v_lshl_add_u64 v[2:3], v[2:3], 0, v[160:161]
	s_or_b32 s0, s2, 0x200
	s_mov_b32 s1, s3
	v_lshl_add_u64 v[2:3], v[2:3], 0, s[0:1]
	s_mov_b32 s14, 0x44000
	v_add_co_u32_e32 v2, vcc, s14, v2
	v_lshl_add_u64 v[4:5], v[4:5], 0, v[160:161]
	s_nop 0
	v_addc_co_u32_e32 v3, vcc, 0, v3, vcc
	global_load_dwordx4 v[104:107], v[4:5], off offset:512
	global_load_dwordx4 v[108:111], v[2:3], off offset:1024
	v_mov_b64_e32 v[2:3], s[12:13]
	v_add_u32_e32 v6, 32, v8
	v_mad_i64_i32 v[4:5], s[10:11], v8, s67, v[2:3]
	v_mad_i64_i32 v[2:3], s[10:11], v6, s67, v[2:3]
	v_add_u32_e32 v6, 64, v7
	v_mad_i64_i32 v[0:1], s[10:11], v6, s33, v[0:1]
	v_lshl_add_u64 v[6:7], v[0:1], 0, s[2:3]
	v_lshl_add_u64 v[0:1], v[0:1], 0, v[160:161]
	v_lshl_add_u64 v[0:1], v[0:1], 0, s[0:1]
	v_lshl_add_u64 v[6:7], v[6:7], 0, v[160:161]
	v_add_co_u32_e32 v0, vcc, s14, v0
	v_lshl_add_u64 v[4:5], v[4:5], 0, v[160:161]
	v_lshl_add_u64 v[2:3], v[2:3], 0, v[160:161]
	v_addc_co_u32_e32 v1, vcc, 0, v1, vcc
	global_load_dwordx4 v[112:115], v[6:7], off offset:512
	global_load_dwordx4 v[116:119], v[0:1], off offset:1024
	global_load_dwordx4 v[120:123], v[4:5], off
	global_load_dwordx4 v[124:127], v[4:5], off offset:128
	global_load_dwordx4 v[128:131], v[2:3], off
	global_load_dwordx4 v[132:135], v[2:3], off offset:128
	s_movk_i32 s0, 0x70
	v_bitop3_b32 v0, v196, s0, v9 bitop3:0x48
	s_movk_i32 s0, 0x88
	v_mul_lo_u32 v2, v8, s0
	s_mul_i32 s0, s9, 0x90000
	s_mul_i32 s1, s6, 0x24000
	s_add_i32 s0, s0, s1
	v_lshlrev_b32_e32 v1, 2, v197
	v_bfe_u32 v4, v196, 1, 3
	s_lshl_b32 s0, s0, 1
	v_lshl_or_b32 v141, v8, 7, v0
	v_lshlrev_b32_e32 v0, 7, v198
	v_or_b32_e32 v3, v1, v171
	v_bitop3_b32 v1, v1, v4, v171 bitop3:0x36
	s_add_u32 s0, s40, s0
	v_lshl_add_u32 v142, v1, 4, v0
	v_bitop3_b32 v1, v3, v4, 2 bitop3:0x36
	s_addc_u32 s1, s41, 0
	v_lshl_add_u32 v143, v1, 4, v0
	v_mov_b64_e32 v[0:1], s[0:1]
	s_mov_b64 s[12:13], s[0:1]
	s_and_b32 s5, s5, 3
	v_mbcnt_hi_u32_b32 v5, -1, v185
	v_mad_i64_i32 v[136:137], s[0:1], v8, s67, v[0:1]
	s_lshl_b32 s5, s5, 7
	v_and_b32_e32 v7, 64, v5
	s_mul_hi_u32 s0, s8, 0x1c71c72
	s_add_u32 s5, s40, s5
	v_xor_b32_e32 v6, 32, v5
	v_add_u32_e32 v7, 64, v7
	s_mul_hi_u32 s1, s0, 0x1332000
	s_mul_i32 s0, s0, 0x1332000
	s_addc_u32 s8, s41, 0
	v_cmp_lt_i32_e32 vcc, v6, v7
	s_add_u32 s0, s5, s0
	s_addc_u32 s1, s8, s1
	v_cndmask_b32_e32 v5, v5, v6, vcc
	v_lshlrev_b32_e32 v170, 2, v5
	v_mul_u32_u24_e32 v5, 0x88, v198
	v_mov_b64_e32 v[0:1], s[0:1]
	s_mov_b64 s[10:11], s[0:1]
	v_mov_b32_e32 v200, 0
	s_mov_b32 s2, 0
	v_mad_i64_i32 v[138:139], s[0:1], v8, s33, v[0:1]
	v_mov_b32_e32 v140, 0xf149f2ca
	v_add_u32_e32 v144, v2, v160
	v_mul_lo_u32 v156, v8, s33
	v_mul_lo_u32 v157, v8, s67
	v_add_u32_e32 v158, 0x2000, v144
	v_add_u32_e32 v159, 0x3100, v144
	v_add_u32_e32 v201, 0x6200, v144
	v_add_u32_e32 v202, 0x7300, v144
	v_add_u32_e32 v156, v156, v160
	v_add_u32_e32 v157, v157, v160
	v_add_u32_e32 v145, v164, v5
	v_add_u32_e32 v236, 0x2000, v145
	v_add_u32_e32 v237, 0x3000, v145
	v_add_u32_e32 v238, 0x6000, v145
	v_add_u32_e32 v239, 0x7000, v145
	v_mov_b32_e32 v16, 0
	v_mov_b32_e32 v17, v200
	v_mov_b32_e32 v18, v200
	v_mov_b32_e32 v19, v200
	v_mov_b32_e32 v20, v200
	v_mov_b32_e32 v21, v200
	v_mov_b32_e32 v22, v200
	v_mov_b32_e32 v23, v200
	v_mov_b32_e32 v24, v200
	v_mov_b32_e32 v25, v200
	v_mov_b32_e32 v26, v200
	v_mov_b32_e32 v27, v200
	v_mov_b32_e32 v28, v200
	v_mov_b32_e32 v29, v200
	v_mov_b32_e32 v30, v200
	v_mov_b32_e32 v31, v200
	v_mov_b32_e32 v0, v200
	v_mov_b32_e32 v1, v200
	v_mov_b32_e32 v2, v200
	v_mov_b32_e32 v3, v200
	v_mov_b32_e32 v4, v200
	v_mov_b32_e32 v5, v200
	v_mov_b32_e32 v6, v200
	v_mov_b32_e32 v7, v200
	v_mov_b32_e32 v8, v200
	v_mov_b32_e32 v9, v200
	v_mov_b32_e32 v10, v200
	v_mov_b32_e32 v11, v200
	v_mov_b32_e32 v12, v200
	v_mov_b32_e32 v13, v200
	v_mov_b32_e32 v14, v200
	v_mov_b32_e32 v15, v200
	s_branch .LBB0_580
	s_nop 0

; #define MFMA32(a, b, c) __builtin_amdgcn_mfma_f32_32x32x16_bf16((a), (b), (c), 0, 0, 0)
; DI int crow(int reg, int h) { return (reg & 3) + 8 * (reg >> 2) + 4 * h; }
; template <int MODE>
; DI void attn_mfma(const Params& p, int l, int b, int hd, int qb, unsigned char* smem) {
;     ...
;     f32x16 SA0, SA1, SB0, SB1;
; #pragma unroll
;     for (int i = 0; i < 16; ++i) { SA0[i] = 0.f; SA1[i] = 0.f; SB0[i] = 0.f; SB1[i] = 0.f; }
; #pragma unroll
;     for (int ks = 0; ks < KS; ++ks) {
;       const int kk = mp * 2 + ks;
;       const int key0 = r, key1 = 32 + r;
;       const int o0 = key0 * 128 + (((2 * kk + h2) ^ ((key0 >> 1) & 7)) << 4), o1 = key1 * 128 + (((2 * kk + h2) ^ ((key1 >> 1) & 7)) << 4);
;       SA0 = MFMA32(*(const bf16x8*)(sK + o0), qf[ks], SA0);
;       SA1 = MFMA32(*(const bf16x8*)(sK + o1), qf[ks], SA1);
;       SB0 = MFMA32(*(const bf16x8*)(sK + 16896 + o0), qf[ks], SB0);
;       SB1 = MFMA32(*(const bf16x8*)(sK + 16896 + o1), qf[ks], SB1);
;     }
; #pragma unroll
;     for (int hf = 0; hf < 2; ++hf) {
;     const unsigned char* sVc = sV + hf * 16896;
;     const int tbcur = tile_base(j + hf);
;     f32x16 S[2];
;     S[0] = hf == 0 ? SA0 : SB0;
;     S[1] = hf == 0 ? SA1 : SB1;
;     if (MODE == 1 && j + hf >= 4) {
;       const int iq = tq - NCTX;
;       const int jb = tbcur - NCTX;
; #pragma unroll
;       for (int mt = 0; mt < 2; ++mt)
; #pragma unroll
;         for (int i = 0; i < 16; ++i) {
;           const int dd = iq - (jb + mt * 32 + crow(i, h2));
;           if (dd > 128 || dd < -128) S[mt][i] = -1e30f;
;         }
;     }
;     float mx = -1e30f;
; #pragma unroll
;     for (int mt = 0; mt < 2; ++mt)
; #pragma unroll
;       for (int i = 0; i < 16; ++i) mx = fmaxf(mx, S[mt][i]);
;     mx = fmaxf(mx, __shfl_xor(mx, 32));
;     const float zmx = mx * cexp;
;     if (__any(zmx > mrun + 8.f)) {
;       const float mnew = fmaxf(mrun, zmx);
;       const float alpha = __builtin_amdgcn_exp2f(mrun - mnew);
;       mrun = mnew;
;       lsum *= alpha;
;       const f32x2 al2 = {alpha, alpha};
; #pragma unroll
;       for (int vt = 0; vt < 2; ++vt)
; #pragma unroll
;         for (int i = 0; i < 8; ++i) {
;           f32x2 o = {O[vt][2 * i], O[vt][2 * i + 1]};
;           o = o * al2;
;           O[vt][2 * i] = o.x; O[vt][2 * i + 1] = o.y;
;         }
;     }
.LBB0_582:
	s_mov_b32 s5, 0xf149f2ca
	s_mov_b32 s8, 0x3e8293ee
	s_waitcnt lgkmcnt(6)
	v_mfma_f32_32x32x16_bf16 v[80:95], v[204:207], v[96:99], 0
	v_mfma_f32_32x32x16_bf16 v[80:95], v[208:211], v[100:103], v[80:95]
	s_waitcnt lgkmcnt(4)
	v_mfma_f32_32x32x16_bf16 v[64:79], v[212:215], v[96:99], 0
	v_mfma_f32_32x32x16_bf16 v[64:79], v[216:219], v[100:103], v[64:79]
	s_waitcnt lgkmcnt(0)
	v_mfma_f32_32x32x16_bf16 v[48:63], v[220:223], v[96:99], 0
	ds_read2_b64 v[204:207], v236 offset1:2
	ds_read2_b64 v[208:211], v237 offset0:32 offset1:34
	ds_read2_b64 v[212:215], v236 offset0:4 offset1:6
	ds_read2_b64 v[216:219], v237 offset0:36 offset1:38
	v_mfma_f32_32x32x16_bf16 v[48:63], v[224:227], v[100:103], v[48:63]
	s_nop 1
	v_max3_f32 v146, v80, s5, v81
	v_max3_f32 v146, v146, v82, v83
	v_max3_f32 v146, v146, v84, v85
	v_max3_f32 v146, v146, v86, v87
	v_max3_f32 v146, v146, v88, v89
	v_max3_f32 v146, v146, v90, v91
	v_max3_f32 v146, v146, v92, v93
	v_max3_f32 v146, v146, v94, v95
	v_mfma_f32_32x32x16_bf16 v[32:47], v[228:231], v[96:99], 0
	v_max3_f32 v146, v146, v64, v65
	v_max3_f32 v146, v146, v66, v67
	v_max3_f32 v146, v146, v68, v69
	v_max3_f32 v146, v146, v70, v71
	v_mfma_f32_32x32x16_bf16 v[32:47], v[232:235], v[100:103], v[32:47]
	v_max3_f32 v146, v146, v72, v73
	v_max3_f32 v146, v146, v74, v75
	v_max3_f32 v146, v146, v76, v77
	v_max3_f32 v146, v146, v78, v79
	v_mov_b32_e64 v147, v146
	s_nop 1
	v_permlane32_swap_b32_e32 v147, v146
	ds_read2_b64 v[220:223], v236 offset0:8 offset1:10
	ds_read2_b64 v[224:227], v237 offset0:40 offset1:42
	ds_read2_b64 v[228:231], v236 offset0:12 offset1:14
	ds_read2_b64 v[232:235], v237 offset0:44 offset1:46
	s_waitcnt lgkmcnt(4)
	v_max_f32_e32 v147, v147, v147
	v_max_f32_e32 v146, v146, v147
	v_mul_f32_e32 v147, 0x3e8293ee, v146
	v_add_f32_e32 v146, 0x41000000, v140
	v_cmp_gt_f32_e32 vcc, v147, v146
	s_cbranch_vccz .Laa_nra
	v_max_f32_e32 v146, v147, v147
	v_max_f32_e32 v147, v140, v140
	v_max_f32_e32 v147, v147, v146
	v_sub_f32_e32 v140, v140, v147
	v_exp_f32_e32 v140, v140
	v_add_f32_e32 v146, 0x41000000, v147
	v_pk_mul_f32 v[18:19], v[18:19], v[140:141] op_sel_hi:[1,0]
	v_pk_mul_f32 v[20:21], v[20:21], v[140:141] op_sel_hi:[1,0]
	v_pk_mul_f32 v[22:23], v[22:23], v[140:141] op_sel_hi:[1,0]
	v_pk_mul_f32 v[24:25], v[24:25], v[140:141] op_sel_hi:[1,0]
	v_pk_mul_f32 v[26:27], v[26:27], v[140:141] op_sel_hi:[1,0]
	v_pk_mul_f32 v[28:29], v[28:29], v[140:141] op_sel_hi:[1,0]
	v_pk_mul_f32 v[16:17], v[16:17], v[140:141] op_sel_hi:[1,0]
	v_pk_mul_f32 v[30:31], v[30:31], v[140:141] op_sel_hi:[1,0]
	v_pk_mul_f32 v[0:1], v[0:1], v[140:141] op_sel_hi:[1,0]
	v_pk_mul_f32 v[2:3], v[2:3], v[140:141] op_sel_hi:[1,0]
	v_pk_mul_f32 v[4:5], v[4:5], v[140:141] op_sel_hi:[1,0]
	v_pk_mul_f32 v[6:7], v[6:7], v[140:141] op_sel_hi:[1,0]
	v_pk_mul_f32 v[8:9], v[8:9], v[140:141] op_sel_hi:[1,0]
	v_pk_mul_f32 v[10:11], v[10:11], v[140:141] op_sel_hi:[1,0]
	v_pk_mul_f32 v[12:13], v[12:13], v[140:141] op_sel_hi:[1,0]
	v_pk_mul_f32 v[14:15], v[14:15], v[140:141] op_sel_hi:[1,0]
	v_mul_f32_e32 v200, v200, v140
	v_mov_b32_e32 v140, v147
